# v025: v024 + same reorder for the second-half LDS fragment reads of the three GEMM loops (literal address adds first, scalar constants after the reads)
# baseline (speedup 1.0000x reference)
; #define PG8_STAGE(bufoff, gbase, voff) do { _Pragma("unroll") for (int _i = 0; _i < 2; ++_i) \
;         __builtin_amdgcn_global_load_lds((const unsigned*)((const char*)(gbase) + (voff)[_i]), (PG8_LAS unsigned*)(lds + (bufoff) + ldsw + _i * 8192), 16, 0, 0); } while (0)
; #define PG8_LDA(dst, b, h) do { _Pragma("unroll") for (int m = 0; m < 4; ++m) _Pragma("unroll") for (int k = 0; k < 2; ++k) dst[m][k] = *(const PG8_LAS bf16x8*)(lds + PG8_SA(b, h) + aoff + m * 2048 + k * 1024); } while (0)
; #define PG8_LDB(dst, b, h) do { _Pragma("unroll") for (int n = 0; n < 2; ++n) _Pragma("unroll") for (int k = 0; k < 2; ++k) dst[n][k] = *(const PG8_LAS bf16x8*)(lds + PG8_SB(b, h) + boff + n * 2048 + k * 1024); } while (0)
; #define PG8_MMA(ai, bj, At, Bt) do { __builtin_amdgcn_s_setprio(1); _Pragma("unroll") for (int m = 0; m < 4; ++m) _Pragma("unroll") for (int n = 0; n < 2; ++n) _Pragma("unroll") for (int k = 0; k < 2; ++k) \
;         acc[ai][bj][m][n] = __builtin_amdgcn_mfma_f32_16x16x32_bf16(Bt[n][k], At[m][k], acc[ai][bj][m][n], 0, 0, 0); __builtin_amdgcn_s_setprio(0); } while (0)
; #define PG8_WAIT_V(n) asm volatile("s_waitcnt vmcnt(" #n ")" ::: "memory")
; #define PG8_BAR __builtin_amdgcn_s_barrier()
; template <class Epi, class Sched, bool ALIGN_EPI = false, bool SP2 = false>
; __device__ __forceinline__ void gemm_phase(PG8_LAS unsigned char* lds, const Gemm g, const Sched& S, const Epi& E, int tid_) {
;     ...
;         for (int t = 0; t < nt; t += 2) {
;             const bool last = (t == nt - 2);
;             const char* a1 = cA + (size_t)(t + 1) * kstep;
;             const char* a2 = last ? nA : cA + (size_t)(t + 2) * kstep; const char* b2 = last ? nB : cB + (size_t)(t + 2) * kstep;
;             const char* a3 = a2 + kstep; const char* b3 = b2 + kstep;
;             if (last && has_next) S.a_ready(nxt);
;             if constexpr (SP2) {
;             PG8_LDB(B0, 0, 0); PG8_LDB(B1, 0, 1); PG8_SCHED; PG8_LDA(At, 0, 0); PG8_STAGE(PG8_SA(1, 1), a1 + hstep, voffA);
;             PG8_WAIT_V(8); PG8_WAIT_L(0); PG8_BAR; PG8_MMA(0, 0, At, B0); PG8_MMA(0, 1, At, B1); PG8_BAR; PG8_SCHED;
;             PG8_LDA(At, 0, 1); PG8_STAGE(PG8_SB(0, 0), b2, voffB); PG8_STAGE(PG8_SB(0, 1), b2 + hstep, voffB); PG8_STAGE(PG8_SA(0, 0), a2, voffA);
;             PG8_WAIT_V(8); PG8_WAIT_L(0); PG8_BAR; PG8_MMA(1, 0, At, B0); PG8_MMA(1, 1, At, B1); PG8_BAR; PG8_SCHED;
.LBB0_226:
	v_add_u32_e32 v140, 0x10000, v143
	ds_read_b128 v[146:149], v140
	ds_read_b128 v[150:153], v140 offset:1024
	ds_read_b128 v[154:157], v140 offset:2048
	ds_read_b128 v[158:161], v140 offset:3072
	v_add_u32_e32 v140, 0x14000, v143
	ds_read_b128 v[162:165], v140
	ds_read_b128 v[166:169], v140 offset:1024
	ds_read_b128 v[170:173], v140 offset:2048
	ds_read_b128 v[174:177], v140 offset:3072
	s_add_i32 s91, s64, 2
	s_add_u32 s21, s70, 0x80
	s_addc_u32 s65, s71, 0
	s_add_i32 s94, 0, 0x10000
	s_cmp_eq_u32 s55, s64
	s_cselect_b32 s65, s43, s65
	s_cselect_b32 s64, s42, s21
	s_cselect_b32 s93, s61, s81
	s_cselect_b32 s92, s60, s80
	s_add_i32 s21, 0, 0x14000
	v_lshl_add_u64 v[140:141], s[70:71], 0, v[138:139]
	s_add_i32 m0, s11, 0xc000
	ds_read_b128 v[178:181], v145
	ds_read_b128 v[182:185], v145 offset:1024
	ds_read_b128 v[186:189], v145 offset:2048
	ds_read_b128 v[200:203], v145 offset:3072
	ds_read_b128 v[204:207], v145 offset:4096
	ds_read_b128 v[208:211], v145 offset:5120
	ds_read_b128 v[214:217], v145 offset:6144
	ds_read_b128 v[232:235], v145 offset:7168
	global_load_lds_dwordx4 v[140:141], off
	v_lshl_add_u64 v[140:141], s[70:71], 0, v[136:137]
	s_add_i32 m0, s11, 0xe000
	s_nop 0
	global_load_lds_dwordx4 v[140:141], off
	s_waitcnt vmcnt(8)
	s_waitcnt lgkmcnt(0)
	s_barrier
	s_setprio 1
	s_waitcnt lgkmcnt(0)
	v_mfma_f32_16x16x32_bf16 v[126:129], v[146:149], v[178:181], v[126:129]
	v_mfma_f32_16x16x32_bf16 v[122:125], v[154:157], v[178:181], v[122:125]
	v_mfma_f32_16x16x32_bf16 v[110:113], v[146:149], v[186:189], v[110:113]
	v_mfma_f32_16x16x32_bf16 v[106:109], v[154:157], v[186:189], v[106:109]
	v_mfma_f32_16x16x32_bf16 v[94:97], v[146:149], v[204:207], v[94:97]
	v_mfma_f32_16x16x32_bf16 v[90:93], v[154:157], v[204:207], v[90:93]
	v_mfma_f32_16x16x32_bf16 v[78:81], v[146:149], v[214:217], v[78:81]
	v_mfma_f32_16x16x32_bf16 v[74:77], v[154:157], v[214:217], v[74:77]
	v_mfma_f32_16x16x32_bf16 v[126:129], v[150:153], v[182:185], v[126:129]
	v_mfma_f32_16x16x32_bf16 v[122:125], v[158:161], v[182:185], v[122:125]
	v_mfma_f32_16x16x32_bf16 v[110:113], v[150:153], v[200:203], v[110:113]
	v_mfma_f32_16x16x32_bf16 v[106:109], v[158:161], v[200:203], v[106:109]
	v_mfma_f32_16x16x32_bf16 v[94:97], v[150:153], v[208:211], v[94:97]
	v_mfma_f32_16x16x32_bf16 v[90:93], v[158:161], v[208:211], v[90:93]
	v_mfma_f32_16x16x32_bf16 v[78:81], v[150:153], v[232:235], v[78:81]
	v_mfma_f32_16x16x32_bf16 v[74:77], v[158:161], v[232:235], v[74:77]
	s_setprio 0
	s_setprio 1
	v_mfma_f32_16x16x32_bf16 v[118:121], v[162:165], v[178:181], v[118:121]
	v_mfma_f32_16x16x32_bf16 v[114:117], v[170:173], v[178:181], v[114:117]
	v_mfma_f32_16x16x32_bf16 v[102:105], v[162:165], v[186:189], v[102:105]
	v_mfma_f32_16x16x32_bf16 v[98:101], v[170:173], v[186:189], v[98:101]
	v_mfma_f32_16x16x32_bf16 v[86:89], v[162:165], v[204:207], v[86:89]
	v_mfma_f32_16x16x32_bf16 v[82:85], v[170:173], v[204:207], v[82:85]
	v_mfma_f32_16x16x32_bf16 v[70:73], v[162:165], v[214:217], v[70:73]
	v_mfma_f32_16x16x32_bf16 v[66:69], v[170:173], v[214:217], v[66:69]
	v_mfma_f32_16x16x32_bf16 v[118:121], v[166:169], v[182:185], v[118:121]
	v_mfma_f32_16x16x32_bf16 v[114:117], v[174:177], v[182:185], v[114:117]
	v_mfma_f32_16x16x32_bf16 v[102:105], v[166:169], v[200:203], v[102:105]
	v_mfma_f32_16x16x32_bf16 v[98:101], v[174:177], v[200:203], v[98:101]
	v_mfma_f32_16x16x32_bf16 v[86:89], v[166:169], v[208:211], v[86:89]
	v_mfma_f32_16x16x32_bf16 v[82:85], v[174:177], v[208:211], v[82:85]
	v_mfma_f32_16x16x32_bf16 v[70:73], v[166:169], v[232:235], v[70:73]
	v_mfma_f32_16x16x32_bf16 v[66:69], v[174:177], v[232:235], v[66:69]
	s_setprio 0
	s_barrier
	s_add_i32 s94, s94, s9
	v_lshl_add_u64 v[140:141], s[92:93], 0, v[0:1]
	s_mov_b32 m0, s94
	ds_read_b128 v[178:181], v145 offset:16384
	ds_read_b128 v[182:185], v145 offset:17408
	ds_read_b128 v[186:189], v145 offset:18432
	ds_read_b128 v[200:203], v145 offset:19456
	ds_read_b128 v[204:207], v145 offset:20480
	ds_read_b128 v[208:211], v145 offset:21504
	ds_read_b128 v[214:217], v145 offset:22528
	ds_read_b128 v[232:235], v145 offset:23552
	global_load_lds_dwordx4 v[140:141], off
	s_add_i32 m0, s94, 0x2000
	v_lshl_add_u64 v[190:191], s[92:93], 0, v[134:135]
	s_add_u32 s92, s92, s38
	s_addc_u32 s93, s93, s39
	s_add_i32 s21, s21, s9
	global_load_lds_dwordx4 v[190:191], off
	v_lshl_add_u64 v[236:237], s[92:93], 0, v[0:1]
	s_mov_b32 m0, s21
	v_lshl_add_u64 v[238:239], s[92:93], 0, v[134:135]
	global_load_lds_dwordx4 v[236:237], off
	s_add_i32 m0, s21, 0x2000
	v_lshl_add_u64 v[240:241], s[64:65], 0, v[130:131]
	global_load_lds_dwordx4 v[238:239], off
	s_mov_b32 m0, s11
	v_lshl_add_u64 v[242:243], s[64:65], 0, v[132:133]
	global_load_lds_dwordx4 v[240:241], off
	s_mov_b32 m0, s12
	s_nop 0
	global_load_lds_dwordx4 v[242:243], off
	s_waitcnt vmcnt(8)
	s_waitcnt lgkmcnt(0)
	s_barrier
; #define PG8_STAGE(bufoff, gbase, voff) do { _Pragma("unroll") for (int _i = 0; _i < 2; ++_i) \
;         __builtin_amdgcn_global_load_lds((const unsigned*)((const char*)(gbase) + (voff)[_i]), (PG8_LAS unsigned*)(lds + (bufoff) + ldsw + _i * 8192), 16, 0, 0); } while (0)
; #define PG8_LDA(dst, b, h) do { _Pragma("unroll") for (int m = 0; m < 4; ++m) _Pragma("unroll") for (int k = 0; k < 2; ++k) dst[m][k] = *(const PG8_LAS bf16x8*)(lds + PG8_SA(b, h) + aoff + m * 2048 + k * 1024); } while (0)
; #define PG8_LDB(dst, b, h) do { _Pragma("unroll") for (int n = 0; n < 2; ++n) _Pragma("unroll") for (int k = 0; k < 2; ++k) dst[n][k] = *(const PG8_LAS bf16x8*)(lds + PG8_SB(b, h) + boff + n * 2048 + k * 1024); } while (0)
; #define PG8_MMA(ai, bj, At, Bt) do { __builtin_amdgcn_s_setprio(1); _Pragma("unroll") for (int m = 0; m < 4; ++m) _Pragma("unroll") for (int n = 0; n < 2; ++n) _Pragma("unroll") for (int k = 0; k < 2; ++k) \
;         acc[ai][bj][m][n] = __builtin_amdgcn_mfma_f32_16x16x32_bf16(Bt[n][k], At[m][k], acc[ai][bj][m][n], 0, 0, 0); __builtin_amdgcn_s_setprio(0); } while (0)
; #define PG8_WAIT_V(n) asm volatile("s_waitcnt vmcnt(" #n ")" ::: "memory")
; #define PG8_WAIT_L(n) asm volatile("s_waitcnt lgkmcnt(" #n ")" ::: "memory")
; #define PG8_BAR __builtin_amdgcn_s_barrier()
; #define PG8_SCHED __builtin_amdgcn_sched_barrier(0)
; template <class Epi, class Sched, bool ALIGN_EPI = false, bool SP2 = false>
; __device__ __forceinline__ void gemm_phase(PG8_LAS unsigned char* lds, const Gemm g, const Sched& S, const Epi& E, int tid_) {
;     ...
;             PG8_WAIT_V(8); PG8_WAIT_L(0); PG8_BAR; PG8_MMA(1, 0, At, B0); PG8_MMA(1, 1, At, B1); PG8_BAR; PG8_SCHED;
;             PG8_LDB(B0, 1, 0); PG8_LDB(B1, 1, 1); PG8_SCHED; PG8_LDA(At, 1, 0); PG8_STAGE(PG8_SA(0, 1), a2 + hstep, voffA);
;             PG8_WAIT_V(8); PG8_WAIT_L(0); PG8_BAR; PG8_MMA(0, 0, At, B0); PG8_MMA(0, 1, At, B1); PG8_BAR; PG8_SCHED;
;             PG8_LDA(At, 1, 1); PG8_STAGE(PG8_SB(1, 0), b3, voffB); PG8_STAGE(PG8_SB(1, 1), b3 + hstep, voffB); PG8_STAGE(PG8_SA(1, 0), a3, voffA);
	s_setprio 1
	s_waitcnt lgkmcnt(0)
	v_mfma_f32_16x16x32_bf16 v[62:65], v[146:149], v[178:181], v[62:65]
	v_mfma_f32_16x16x32_bf16 v[58:61], v[154:157], v[178:181], v[58:61]
	v_mfma_f32_16x16x32_bf16 v[46:49], v[146:149], v[186:189], v[46:49]
	v_mfma_f32_16x16x32_bf16 v[42:45], v[154:157], v[186:189], v[42:45]
	v_mfma_f32_16x16x32_bf16 v[30:33], v[146:149], v[204:207], v[30:33]
	v_mfma_f32_16x16x32_bf16 v[26:29], v[154:157], v[204:207], v[26:29]
	v_mfma_f32_16x16x32_bf16 v[14:17], v[146:149], v[214:217], v[14:17]
	v_mfma_f32_16x16x32_bf16 v[10:13], v[154:157], v[214:217], v[10:13]
	v_mfma_f32_16x16x32_bf16 v[62:65], v[150:153], v[182:185], v[62:65]
	v_mfma_f32_16x16x32_bf16 v[58:61], v[158:161], v[182:185], v[58:61]
	v_mfma_f32_16x16x32_bf16 v[46:49], v[150:153], v[200:203], v[46:49]
	v_mfma_f32_16x16x32_bf16 v[42:45], v[158:161], v[200:203], v[42:45]
	v_mfma_f32_16x16x32_bf16 v[30:33], v[150:153], v[208:211], v[30:33]
	v_mfma_f32_16x16x32_bf16 v[26:29], v[158:161], v[208:211], v[26:29]
	v_mfma_f32_16x16x32_bf16 v[14:17], v[150:153], v[232:235], v[14:17]
	v_mfma_f32_16x16x32_bf16 v[10:13], v[158:161], v[232:235], v[10:13]
	s_setprio 0
	s_setprio 1
	v_mfma_f32_16x16x32_bf16 v[54:57], v[162:165], v[178:181], v[54:57]
	v_mfma_f32_16x16x32_bf16 v[50:53], v[170:173], v[178:181], v[50:53]
	v_mfma_f32_16x16x32_bf16 v[38:41], v[162:165], v[186:189], v[38:41]
	v_mfma_f32_16x16x32_bf16 v[34:37], v[170:173], v[186:189], v[34:37]
	v_mfma_f32_16x16x32_bf16 v[22:25], v[162:165], v[204:207], v[22:25]
	v_mfma_f32_16x16x32_bf16 v[18:21], v[170:173], v[204:207], v[18:21]
	v_mfma_f32_16x16x32_bf16 v[6:9], v[162:165], v[214:217], v[6:9]
	v_mfma_f32_16x16x32_bf16 v[2:5], v[170:173], v[214:217], v[2:5]
	v_mfma_f32_16x16x32_bf16 v[54:57], v[166:169], v[182:185], v[54:57]
	v_mfma_f32_16x16x32_bf16 v[50:53], v[174:177], v[182:185], v[50:53]
	v_mfma_f32_16x16x32_bf16 v[38:41], v[166:169], v[200:203], v[38:41]
	v_mfma_f32_16x16x32_bf16 v[34:37], v[174:177], v[200:203], v[34:37]
	v_mfma_f32_16x16x32_bf16 v[22:25], v[166:169], v[208:211], v[22:25]
	v_mfma_f32_16x16x32_bf16 v[18:21], v[174:177], v[208:211], v[18:21]
	v_mfma_f32_16x16x32_bf16 v[6:9], v[166:169], v[232:235], v[6:9]
	v_mfma_f32_16x16x32_bf16 v[2:5], v[174:177], v[232:235], v[2:5]
	s_setprio 0
	s_barrier
	v_add_u32_e32 v158, 0x18000, v143
	v_add_u32_e32 v174, 0x1c000, v143
	ds_read_b128 v[146:149], v158
	ds_read_b128 v[150:153], v158 offset:1024
	ds_read_b128 v[154:157], v158 offset:2048
	ds_read_b128 v[158:161], v158 offset:3072
	ds_read_b128 v[162:165], v174
	ds_read_b128 v[166:169], v174 offset:1024
	ds_read_b128 v[170:173], v174 offset:2048
	ds_read_b128 v[174:177], v174 offset:3072
	s_add_i32 s21, 0, 0x18000
	s_add_i32 s92, 0, 0x1c000
	s_add_u32 s64, s64, s38
	s_addc_u32 s65, s65, s39
	s_mov_b32 m0, s13
	v_lshl_add_u64 v[244:245], s[64:65], 0, v[130:131]
	ds_read_b128 v[178:181], v145 offset:32768
	ds_read_b128 v[182:185], v145 offset:33792
	ds_read_b128 v[186:189], v145 offset:34816
	ds_read_b128 v[200:203], v145 offset:35840
	ds_read_b128 v[204:207], v145 offset:36864
	ds_read_b128 v[208:211], v145 offset:37888
	ds_read_b128 v[214:217], v145 offset:38912
	ds_read_b128 v[232:235], v145 offset:39936
	global_load_lds_dwordx4 v[244:245], off
	v_lshl_add_u64 v[244:245], s[64:65], 0, v[132:133]
	s_mov_b32 m0, s14
	s_nop 0
	global_load_lds_dwordx4 v[244:245], off
	s_waitcnt vmcnt(8)
	s_waitcnt lgkmcnt(0)
	s_barrier
	s_setprio 1
	s_waitcnt lgkmcnt(0)
	v_mfma_f32_16x16x32_bf16 v[126:129], v[146:149], v[178:181], v[126:129]
	v_mfma_f32_16x16x32_bf16 v[122:125], v[154:157], v[178:181], v[122:125]
	v_mfma_f32_16x16x32_bf16 v[110:113], v[146:149], v[186:189], v[110:113]
	v_mfma_f32_16x16x32_bf16 v[106:109], v[154:157], v[186:189], v[106:109]
	v_mfma_f32_16x16x32_bf16 v[94:97], v[146:149], v[204:207], v[94:97]
	v_mfma_f32_16x16x32_bf16 v[90:93], v[154:157], v[204:207], v[90:93]
	v_mfma_f32_16x16x32_bf16 v[78:81], v[146:149], v[214:217], v[78:81]
	v_mfma_f32_16x16x32_bf16 v[74:77], v[154:157], v[214:217], v[74:77]
	v_mfma_f32_16x16x32_bf16 v[126:129], v[150:153], v[182:185], v[126:129]
	v_mfma_f32_16x16x32_bf16 v[122:125], v[158:161], v[182:185], v[122:125]
	v_mfma_f32_16x16x32_bf16 v[110:113], v[150:153], v[200:203], v[110:113]
	v_mfma_f32_16x16x32_bf16 v[106:109], v[158:161], v[200:203], v[106:109]
	v_mfma_f32_16x16x32_bf16 v[94:97], v[150:153], v[208:211], v[94:97]
	v_mfma_f32_16x16x32_bf16 v[90:93], v[158:161], v[208:211], v[90:93]
	v_mfma_f32_16x16x32_bf16 v[78:81], v[150:153], v[232:235], v[78:81]
	v_mfma_f32_16x16x32_bf16 v[74:77], v[158:161], v[232:235], v[74:77]
	s_setprio 0
	s_setprio 1
	v_mfma_f32_16x16x32_bf16 v[118:121], v[162:165], v[178:181], v[118:121]
	v_mfma_f32_16x16x32_bf16 v[114:117], v[170:173], v[178:181], v[114:117]
	v_mfma_f32_16x16x32_bf16 v[102:105], v[162:165], v[186:189], v[102:105]
	v_mfma_f32_16x16x32_bf16 v[98:101], v[170:173], v[186:189], v[98:101]
	v_mfma_f32_16x16x32_bf16 v[86:89], v[162:165], v[204:207], v[86:89]
	v_mfma_f32_16x16x32_bf16 v[82:85], v[170:173], v[204:207], v[82:85]
	v_mfma_f32_16x16x32_bf16 v[70:73], v[162:165], v[214:217], v[70:73]
	v_mfma_f32_16x16x32_bf16 v[66:69], v[170:173], v[214:217], v[66:69]
	v_mfma_f32_16x16x32_bf16 v[118:121], v[166:169], v[182:185], v[118:121]
	v_mfma_f32_16x16x32_bf16 v[114:117], v[174:177], v[182:185], v[114:117]
	v_mfma_f32_16x16x32_bf16 v[102:105], v[166:169], v[200:203], v[102:105]
	v_mfma_f32_16x16x32_bf16 v[98:101], v[174:177], v[200:203], v[98:101]
	v_mfma_f32_16x16x32_bf16 v[86:89], v[166:169], v[208:211], v[86:89]
	v_mfma_f32_16x16x32_bf16 v[82:85], v[174:177], v[208:211], v[82:85]
	v_mfma_f32_16x16x32_bf16 v[70:73], v[166:169], v[232:235], v[70:73]
	v_mfma_f32_16x16x32_bf16 v[66:69], v[174:177], v[232:235], v[66:69]
	s_setprio 0
	s_barrier
; #define PG8_STAGE(bufoff, gbase, voff) do { _Pragma("unroll") for (int _i = 0; _i < 2; ++_i) \
;         __builtin_amdgcn_global_load_lds((const unsigned*)((const char*)(gbase) + (voff)[_i]), (PG8_LAS unsigned*)(lds + (bufoff) + ldsw + _i * 8192), 16, 0, 0); } while (0)
; #define PG8_LDA(dst, b, h) do { _Pragma("unroll") for (int m = 0; m < 4; ++m) _Pragma("unroll") for (int k = 0; k < 2; ++k) dst[m][k] = *(const PG8_LAS bf16x8*)(lds + PG8_SA(b, h) + aoff + m * 2048 + k * 1024); } while (0)
; #define PG8_MMA(ai, bj, At, Bt) do { __builtin_amdgcn_s_setprio(1); _Pragma("unroll") for (int m = 0; m < 4; ++m) _Pragma("unroll") for (int n = 0; n < 2; ++n) _Pragma("unroll") for (int k = 0; k < 2; ++k) \
;         acc[ai][bj][m][n] = __builtin_amdgcn_mfma_f32_16x16x32_bf16(Bt[n][k], At[m][k], acc[ai][bj][m][n], 0, 0, 0); __builtin_amdgcn_s_setprio(0); } while (0)
; #define PG8_WAIT_V(n) asm volatile("s_waitcnt vmcnt(" #n ")" ::: "memory")
; #define PG8_WAIT_L(n) asm volatile("s_waitcnt lgkmcnt(" #n ")" ::: "memory")
; #define PG8_BAR __builtin_amdgcn_s_barrier()
; #define PG8_SCHED __builtin_amdgcn_sched_barrier(0)
; template <class Epi, class Sched, bool ALIGN_EPI = false, bool SP2 = false>
; __device__ __forceinline__ void gemm_phase(PG8_LAS unsigned char* lds, const Gemm g, const Sched& S, const Epi& E, int tid_) {
;     ...
;             PG8_LDA(At, 1, 1); PG8_STAGE(PG8_SB(1, 0), b3, voffB); PG8_STAGE(PG8_SB(1, 1), b3 + hstep, voffB); PG8_STAGE(PG8_SA(1, 0), a3, voffA);
;             PG8_WAIT_V(8); PG8_WAIT_L(0); PG8_BAR; PG8_MMA(1, 0, At, B0); PG8_MMA(1, 1, At, B1); PG8_BAR; PG8_SCHED;
;     ...
;         if constexpr (ALIGN_EPI) { if (wr == 0) PG8_BAR; }
	s_add_i32 s21, s21, s9
	v_lshl_add_u64 v[140:141], v[140:141], 0, s[28:29]
	s_mov_b32 m0, s21
	ds_read_b128 v[178:181], v145 offset:49152
	ds_read_b128 v[182:185], v145 offset:50176
	ds_read_b128 v[186:189], v145 offset:51200
	ds_read_b128 v[200:203], v145 offset:52224
	ds_read_b128 v[204:207], v145 offset:53248
	ds_read_b128 v[208:211], v145 offset:54272
	ds_read_b128 v[214:217], v145 offset:55296
	ds_read_b128 v[232:235], v145 offset:56320
	global_load_lds_dwordx4 v[140:141], off
	v_lshl_add_u64 v[140:141], v[190:191], 0, s[28:29]
	s_add_i32 m0, s21, 0x2000
	s_add_i32 s21, s92, s9
	global_load_lds_dwordx4 v[140:141], off
	v_lshl_add_u64 v[140:141], v[236:237], 0, s[28:29]
	s_mov_b32 m0, s21
	s_nop 0
	global_load_lds_dwordx4 v[140:141], off
	v_lshl_add_u64 v[140:141], v[238:239], 0, s[28:29]
	s_add_i32 m0, s21, 0x2000
	s_nop 0
	global_load_lds_dwordx4 v[140:141], off
	v_lshl_add_u64 v[140:141], v[240:241], 0, s[28:29]
	s_mov_b32 m0, s37
	s_nop 0
	global_load_lds_dwordx4 v[140:141], off
	v_lshl_add_u64 v[140:141], v[242:243], 0, s[28:29]
	s_mov_b32 m0, s69
	s_nop 0
	global_load_lds_dwordx4 v[140:141], off
	s_waitcnt vmcnt(8)
	s_waitcnt lgkmcnt(0)
	s_barrier
	s_setprio 1
	s_waitcnt lgkmcnt(0)
	v_mfma_f32_16x16x32_bf16 v[62:65], v[146:149], v[178:181], v[62:65]
	v_mfma_f32_16x16x32_bf16 v[58:61], v[154:157], v[178:181], v[58:61]
	v_mfma_f32_16x16x32_bf16 v[46:49], v[146:149], v[186:189], v[46:49]
	v_mfma_f32_16x16x32_bf16 v[42:45], v[154:157], v[186:189], v[42:45]
	v_mfma_f32_16x16x32_bf16 v[30:33], v[146:149], v[204:207], v[30:33]
	v_mfma_f32_16x16x32_bf16 v[26:29], v[154:157], v[204:207], v[26:29]
	v_mfma_f32_16x16x32_bf16 v[14:17], v[146:149], v[214:217], v[14:17]
	v_mfma_f32_16x16x32_bf16 v[10:13], v[154:157], v[214:217], v[10:13]
	v_mfma_f32_16x16x32_bf16 v[62:65], v[150:153], v[182:185], v[62:65]
	v_mfma_f32_16x16x32_bf16 v[58:61], v[158:161], v[182:185], v[58:61]
	v_mfma_f32_16x16x32_bf16 v[46:49], v[150:153], v[200:203], v[46:49]
	v_mfma_f32_16x16x32_bf16 v[42:45], v[158:161], v[200:203], v[42:45]
	v_mfma_f32_16x16x32_bf16 v[30:33], v[150:153], v[208:211], v[30:33]
	v_mfma_f32_16x16x32_bf16 v[26:29], v[158:161], v[208:211], v[26:29]
	v_mfma_f32_16x16x32_bf16 v[14:17], v[150:153], v[232:235], v[14:17]
	v_mfma_f32_16x16x32_bf16 v[10:13], v[158:161], v[232:235], v[10:13]
	s_setprio 0
	s_setprio 1
	v_mfma_f32_16x16x32_bf16 v[54:57], v[162:165], v[178:181], v[54:57]
	v_mfma_f32_16x16x32_bf16 v[50:53], v[170:173], v[178:181], v[50:53]
	v_mfma_f32_16x16x32_bf16 v[38:41], v[162:165], v[186:189], v[38:41]
	v_mfma_f32_16x16x32_bf16 v[34:37], v[170:173], v[186:189], v[34:37]
	v_mfma_f32_16x16x32_bf16 v[22:25], v[162:165], v[204:207], v[22:25]
	v_mfma_f32_16x16x32_bf16 v[18:21], v[170:173], v[204:207], v[18:21]
	v_mfma_f32_16x16x32_bf16 v[6:9], v[162:165], v[214:217], v[6:9]
	v_mfma_f32_16x16x32_bf16 v[2:5], v[170:173], v[214:217], v[2:5]
	v_mfma_f32_16x16x32_bf16 v[54:57], v[166:169], v[182:185], v[54:57]
	v_mfma_f32_16x16x32_bf16 v[50:53], v[174:177], v[182:185], v[50:53]
	v_mfma_f32_16x16x32_bf16 v[38:41], v[166:169], v[200:203], v[38:41]
	v_mfma_f32_16x16x32_bf16 v[34:37], v[174:177], v[200:203], v[34:37]
	v_mfma_f32_16x16x32_bf16 v[22:25], v[166:169], v[208:211], v[22:25]
	v_mfma_f32_16x16x32_bf16 v[18:21], v[174:177], v[208:211], v[18:21]
	v_mfma_f32_16x16x32_bf16 v[6:9], v[166:169], v[232:235], v[6:9]
	v_mfma_f32_16x16x32_bf16 v[2:5], v[174:177], v[232:235], v[2:5]
	s_setprio 0
	s_barrier
	s_add_u32 s80, s80, 0x100
	s_addc_u32 s81, s81, 0
	s_add_u32 s70, s70, 0x100
	s_addc_u32 s71, s71, 0
	s_cmp_ge_i32 s91, s90
	s_mov_b32 s64, s91
	s_cbranch_scc0 .LBB0_226
	s_and_b64 vcc, exec, s[50:51]
	s_cbranch_vccz .LBB0_229
	s_barrier

; #define PG8_STAGE(bufoff, gbase, voff) do { _Pragma("unroll") for (int _i = 0; _i < 2; ++_i) \
;         __builtin_amdgcn_global_load_lds((const unsigned*)((const char*)(gbase) + (voff)[_i]), (PG8_LAS unsigned*)(lds + (bufoff) + ldsw + _i * 8192), 16, 0, 0); } while (0)
; #define PG8_LDA(dst, b, h) do { _Pragma("unroll") for (int m = 0; m < 4; ++m) _Pragma("unroll") for (int k = 0; k < 2; ++k) dst[m][k] = *(const PG8_LAS bf16x8*)(lds + PG8_SA(b, h) + aoff + m * 2048 + k * 1024); } while (0)
; #define PG8_LDB(dst, b, h) do { _Pragma("unroll") for (int n = 0; n < 2; ++n) _Pragma("unroll") for (int k = 0; k < 2; ++k) dst[n][k] = *(const PG8_LAS bf16x8*)(lds + PG8_SB(b, h) + boff + n * 2048 + k * 1024); } while (0)
; #define PG8_MMA(ai, bj, At, Bt) do { __builtin_amdgcn_s_setprio(1); _Pragma("unroll") for (int m = 0; m < 4; ++m) _Pragma("unroll") for (int n = 0; n < 2; ++n) _Pragma("unroll") for (int k = 0; k < 2; ++k) \
;         acc[ai][bj][m][n] = __builtin_amdgcn_mfma_f32_16x16x32_bf16(Bt[n][k], At[m][k], acc[ai][bj][m][n], 0, 0, 0); __builtin_amdgcn_s_setprio(0); } while (0)
; #define PG8_WAIT_V(n) asm volatile("s_waitcnt vmcnt(" #n ")" ::: "memory")
; #define PG8_WAIT_L(n) asm volatile("s_waitcnt lgkmcnt(" #n ")" ::: "memory")
; template <class Epi, class Sched, bool ALIGN_EPI = false, bool SP2 = false>
; __device__ __forceinline__ void gemm_phase(PG8_LAS unsigned char* lds, const Gemm g, const Sched& S, const Epi& E, int tid_) {
;     ...
;             const bool last = (t == nt - 2);
;             const char* a1 = cA + (size_t)(t + 1) * kstep;
;             const char* a2 = last ? nA : cA + (size_t)(t + 2) * kstep; const char* b2 = last ? nB : cB + (size_t)(t + 2) * kstep;
;             const char* a3 = a2 + kstep; const char* b3 = b2 + kstep;
;             if (last && has_next) S.a_ready(nxt);
;             if constexpr (SP2) {
;             PG8_LDB(B0, 0, 0); PG8_LDB(B1, 0, 1); PG8_SCHED; PG8_LDA(At, 0, 0); PG8_STAGE(PG8_SA(1, 1), a1 + hstep, voffA);
;             PG8_WAIT_V(8); PG8_WAIT_L(0); PG8_BAR; PG8_MMA(0, 0, At, B0); PG8_MMA(0, 1, At, B1); PG8_BAR; PG8_SCHED;
;             PG8_LDA(At, 0, 1); PG8_STAGE(PG8_SB(0, 0), b2, voffB); PG8_STAGE(PG8_SB(0, 1), b2 + hstep, voffB); PG8_STAGE(PG8_SA(0, 0), a2, voffA);
;             PG8_WAIT_V(8); PG8_WAIT_L(0); PG8_BAR; PG8_MMA(1, 0, At, B0); PG8_MMA(1, 1, At, B1); PG8_BAR; PG8_SCHED;
.LBB0_438:
	v_add_u32_e32 v142, 0x10000, v199
	v_add_u32_e32 v168, 0x14000, v199
	ds_read_b128 v[130:133], v142
	ds_read_b128 v[134:137], v142 offset:1024
	ds_read_b128 v[138:141], v142 offset:2048
	ds_read_b128 v[142:145], v142 offset:3072
	ds_read_b128 v[146:149], v168
	ds_read_b128 v[150:153], v168 offset:1024
	ds_read_b128 v[154:157], v168 offset:2048
	ds_read_b128 v[168:171], v168 offset:3072
	s_add_i32 s74, s64, 2
	s_add_u32 s13, vcc_lo, 0x80
	s_addc_u32 s14, vcc_hi, 0
	s_add_i32 s75, 0, 0x10000
	s_cmp_eq_u32 s73, s64
	s_cselect_b32 s65, s23, s14
	s_cselect_b32 s64, s22, s13
	s_cselect_b32 s91, s61, s81
	s_cselect_b32 s90, s60, s80
	s_add_i32 s13, 0, 0x14000
	v_lshl_add_u64 v[232:233], vcc, 0, v[166:167]
	s_add_i32 m0, s93, 0xc000
	ds_read_b128 v[172:175], v210
	ds_read_b128 v[176:179], v210 offset:1024
	ds_read_b128 v[180:183], v210 offset:2048
	ds_read_b128 v[184:187], v210 offset:3072
	ds_read_b128 v[188:191], v210 offset:4096
	ds_read_b128 v[200:203], v210 offset:5120
	ds_read_b128 v[204:207], v210 offset:6144
	ds_read_b128 v[214:217], v210 offset:7168
	global_load_lds_dwordx4 v[232:233], off
	v_lshl_add_u64 v[232:233], vcc, 0, v[164:165]
	s_add_i32 m0, s93, 0xe000
	s_nop 0
	global_load_lds_dwordx4 v[232:233], off
	s_waitcnt vmcnt(8)
	s_waitcnt lgkmcnt(0)
	s_barrier
	s_setprio 1
	s_waitcnt lgkmcnt(0)
	v_mfma_f32_16x16x32_bf16 v[126:129], v[130:133], v[172:175], v[126:129]
	v_mfma_f32_16x16x32_bf16 v[122:125], v[138:141], v[172:175], v[122:125]
	v_mfma_f32_16x16x32_bf16 v[110:113], v[130:133], v[180:183], v[110:113]
	v_mfma_f32_16x16x32_bf16 v[106:109], v[138:141], v[180:183], v[106:109]
	v_mfma_f32_16x16x32_bf16 v[94:97], v[130:133], v[188:191], v[94:97]
	v_mfma_f32_16x16x32_bf16 v[90:93], v[138:141], v[188:191], v[90:93]
	v_mfma_f32_16x16x32_bf16 v[78:81], v[130:133], v[204:207], v[78:81]
	v_mfma_f32_16x16x32_bf16 v[74:77], v[138:141], v[204:207], v[74:77]
	v_mfma_f32_16x16x32_bf16 v[126:129], v[134:137], v[176:179], v[126:129]
	v_mfma_f32_16x16x32_bf16 v[122:125], v[142:145], v[176:179], v[122:125]
	v_mfma_f32_16x16x32_bf16 v[110:113], v[134:137], v[184:187], v[110:113]
	v_mfma_f32_16x16x32_bf16 v[106:109], v[142:145], v[184:187], v[106:109]
	v_mfma_f32_16x16x32_bf16 v[94:97], v[134:137], v[200:203], v[94:97]
	v_mfma_f32_16x16x32_bf16 v[90:93], v[142:145], v[200:203], v[90:93]
	v_mfma_f32_16x16x32_bf16 v[78:81], v[134:137], v[214:217], v[78:81]
	v_mfma_f32_16x16x32_bf16 v[74:77], v[142:145], v[214:217], v[74:77]
	s_setprio 0
	s_setprio 1
	v_mfma_f32_16x16x32_bf16 v[118:121], v[146:149], v[172:175], v[118:121]
	v_mfma_f32_16x16x32_bf16 v[114:117], v[154:157], v[172:175], v[114:117]
	v_mfma_f32_16x16x32_bf16 v[102:105], v[146:149], v[180:183], v[102:105]
	v_mfma_f32_16x16x32_bf16 v[98:101], v[154:157], v[180:183], v[98:101]
	v_mfma_f32_16x16x32_bf16 v[86:89], v[146:149], v[188:191], v[86:89]
	v_mfma_f32_16x16x32_bf16 v[82:85], v[154:157], v[188:191], v[82:85]
	v_mfma_f32_16x16x32_bf16 v[70:73], v[146:149], v[204:207], v[70:73]
	v_mfma_f32_16x16x32_bf16 v[66:69], v[154:157], v[204:207], v[66:69]
	v_mfma_f32_16x16x32_bf16 v[118:121], v[150:153], v[176:179], v[118:121]
	v_mfma_f32_16x16x32_bf16 v[114:117], v[168:171], v[176:179], v[114:117]
	v_mfma_f32_16x16x32_bf16 v[102:105], v[150:153], v[184:187], v[102:105]
	v_mfma_f32_16x16x32_bf16 v[98:101], v[168:171], v[184:187], v[98:101]
	v_mfma_f32_16x16x32_bf16 v[86:89], v[150:153], v[200:203], v[86:89]
	v_mfma_f32_16x16x32_bf16 v[82:85], v[168:171], v[200:203], v[82:85]
	v_mfma_f32_16x16x32_bf16 v[70:73], v[150:153], v[214:217], v[70:73]
	v_mfma_f32_16x16x32_bf16 v[66:69], v[168:171], v[214:217], v[66:69]
	s_setprio 0
	s_barrier
	s_add_i32 s14, s75, s92
	v_lshl_add_u64 v[232:233], s[90:91], 0, v[0:1]
	s_mov_b32 m0, s14
	ds_read_b128 v[172:175], v210 offset:16384
	ds_read_b128 v[176:179], v210 offset:17408
	ds_read_b128 v[180:183], v210 offset:18432
	ds_read_b128 v[184:187], v210 offset:19456
	ds_read_b128 v[188:191], v210 offset:20480
	ds_read_b128 v[200:203], v210 offset:21504
	ds_read_b128 v[204:207], v210 offset:22528
	ds_read_b128 v[214:217], v210 offset:23552
	global_load_lds_dwordx4 v[232:233], off
	s_add_i32 m0, s14, 0x2000
	v_lshl_add_u64 v[234:235], s[90:91], 0, v[162:163]
	s_add_u32 s90, s90, s50
	s_addc_u32 s91, s91, s51
	s_add_i32 s13, s13, s92
	global_load_lds_dwordx4 v[234:235], off
	v_lshl_add_u64 v[236:237], s[90:91], 0, v[0:1]
	s_mov_b32 m0, s13
	v_lshl_add_u64 v[238:239], s[90:91], 0, v[162:163]
	global_load_lds_dwordx4 v[236:237], off
	s_add_i32 m0, s13, 0x2000
	v_lshl_add_u64 v[240:241], s[64:65], 0, v[158:159]
	global_load_lds_dwordx4 v[238:239], off
	s_mov_b32 m0, s93
	v_lshl_add_u64 v[242:243], s[64:65], 0, v[160:161]
	global_load_lds_dwordx4 v[240:241], off
	s_mov_b32 m0, s94
	s_nop 0
	global_load_lds_dwordx4 v[242:243], off
	s_waitcnt vmcnt(8)
	s_waitcnt lgkmcnt(0)
	s_barrier
; #define PG8_STAGE(bufoff, gbase, voff) do { _Pragma("unroll") for (int _i = 0; _i < 2; ++_i) \
;         __builtin_amdgcn_global_load_lds((const unsigned*)((const char*)(gbase) + (voff)[_i]), (PG8_LAS unsigned*)(lds + (bufoff) + ldsw + _i * 8192), 16, 0, 0); } while (0)
; #define PG8_LDA(dst, b, h) do { _Pragma("unroll") for (int m = 0; m < 4; ++m) _Pragma("unroll") for (int k = 0; k < 2; ++k) dst[m][k] = *(const PG8_LAS bf16x8*)(lds + PG8_SA(b, h) + aoff + m * 2048 + k * 1024); } while (0)
; #define PG8_LDB(dst, b, h) do { _Pragma("unroll") for (int n = 0; n < 2; ++n) _Pragma("unroll") for (int k = 0; k < 2; ++k) dst[n][k] = *(const PG8_LAS bf16x8*)(lds + PG8_SB(b, h) + boff + n * 2048 + k * 1024); } while (0)
; #define PG8_MMA(ai, bj, At, Bt) do { __builtin_amdgcn_s_setprio(1); _Pragma("unroll") for (int m = 0; m < 4; ++m) _Pragma("unroll") for (int n = 0; n < 2; ++n) _Pragma("unroll") for (int k = 0; k < 2; ++k) \
;         acc[ai][bj][m][n] = __builtin_amdgcn_mfma_f32_16x16x32_bf16(Bt[n][k], At[m][k], acc[ai][bj][m][n], 0, 0, 0); __builtin_amdgcn_s_setprio(0); } while (0)
; #define PG8_WAIT_V(n) asm volatile("s_waitcnt vmcnt(" #n ")" ::: "memory")
; #define PG8_WAIT_L(n) asm volatile("s_waitcnt lgkmcnt(" #n ")" ::: "memory")
; #define PG8_BAR __builtin_amdgcn_s_barrier()
; #define PG8_SCHED __builtin_amdgcn_sched_barrier(0)
; template <class Epi, class Sched, bool ALIGN_EPI = false, bool SP2 = false>
; __device__ __forceinline__ void gemm_phase(PG8_LAS unsigned char* lds, const Gemm g, const Sched& S, const Epi& E, int tid_) {
;     ...
;             PG8_WAIT_V(8); PG8_WAIT_L(0); PG8_BAR; PG8_MMA(1, 0, At, B0); PG8_MMA(1, 1, At, B1); PG8_BAR; PG8_SCHED;
;             PG8_LDB(B0, 1, 0); PG8_LDB(B1, 1, 1); PG8_SCHED; PG8_LDA(At, 1, 0); PG8_STAGE(PG8_SA(0, 1), a2 + hstep, voffA);
;             PG8_WAIT_V(8); PG8_WAIT_L(0); PG8_BAR; PG8_MMA(0, 0, At, B0); PG8_MMA(0, 1, At, B1); PG8_BAR; PG8_SCHED;
	s_setprio 1
	s_waitcnt lgkmcnt(0)
	v_mfma_f32_16x16x32_bf16 v[62:65], v[130:133], v[172:175], v[62:65]
	v_mfma_f32_16x16x32_bf16 v[58:61], v[138:141], v[172:175], v[58:61]
	v_mfma_f32_16x16x32_bf16 v[46:49], v[130:133], v[180:183], v[46:49]
	v_mfma_f32_16x16x32_bf16 v[42:45], v[138:141], v[180:183], v[42:45]
	v_mfma_f32_16x16x32_bf16 v[30:33], v[130:133], v[188:191], v[30:33]
	v_mfma_f32_16x16x32_bf16 v[26:29], v[138:141], v[188:191], v[26:29]
	v_mfma_f32_16x16x32_bf16 v[14:17], v[130:133], v[204:207], v[14:17]
	v_mfma_f32_16x16x32_bf16 v[10:13], v[138:141], v[204:207], v[10:13]
	v_mfma_f32_16x16x32_bf16 v[62:65], v[134:137], v[176:179], v[62:65]
	v_mfma_f32_16x16x32_bf16 v[58:61], v[142:145], v[176:179], v[58:61]
	v_mfma_f32_16x16x32_bf16 v[46:49], v[134:137], v[184:187], v[46:49]
	v_mfma_f32_16x16x32_bf16 v[42:45], v[142:145], v[184:187], v[42:45]
	v_mfma_f32_16x16x32_bf16 v[30:33], v[134:137], v[200:203], v[30:33]
	v_mfma_f32_16x16x32_bf16 v[26:29], v[142:145], v[200:203], v[26:29]
	v_mfma_f32_16x16x32_bf16 v[14:17], v[134:137], v[214:217], v[14:17]
	v_mfma_f32_16x16x32_bf16 v[10:13], v[142:145], v[214:217], v[10:13]
	s_setprio 0
	s_setprio 1
	v_mfma_f32_16x16x32_bf16 v[54:57], v[146:149], v[172:175], v[54:57]
	v_mfma_f32_16x16x32_bf16 v[50:53], v[154:157], v[172:175], v[50:53]
	v_mfma_f32_16x16x32_bf16 v[38:41], v[146:149], v[180:183], v[38:41]
	v_mfma_f32_16x16x32_bf16 v[34:37], v[154:157], v[180:183], v[34:37]
	v_mfma_f32_16x16x32_bf16 v[22:25], v[146:149], v[188:191], v[22:25]
	v_mfma_f32_16x16x32_bf16 v[18:21], v[154:157], v[188:191], v[18:21]
	v_mfma_f32_16x16x32_bf16 v[6:9], v[146:149], v[204:207], v[6:9]
	v_mfma_f32_16x16x32_bf16 v[2:5], v[154:157], v[204:207], v[2:5]
	v_mfma_f32_16x16x32_bf16 v[54:57], v[150:153], v[176:179], v[54:57]
	v_mfma_f32_16x16x32_bf16 v[50:53], v[168:171], v[176:179], v[50:53]
	v_mfma_f32_16x16x32_bf16 v[38:41], v[150:153], v[184:187], v[38:41]
	v_mfma_f32_16x16x32_bf16 v[34:37], v[168:171], v[184:187], v[34:37]
	v_mfma_f32_16x16x32_bf16 v[22:25], v[150:153], v[200:203], v[22:25]
	v_mfma_f32_16x16x32_bf16 v[18:21], v[168:171], v[200:203], v[18:21]
	v_mfma_f32_16x16x32_bf16 v[6:9], v[150:153], v[214:217], v[6:9]
	v_mfma_f32_16x16x32_bf16 v[2:5], v[168:171], v[214:217], v[2:5]
	s_setprio 0
	s_barrier
	v_add_u32_e32 v142, 0x18000, v199
	v_add_u32_e32 v168, 0x1c000, v199
	ds_read_b128 v[130:133], v142
	ds_read_b128 v[134:137], v142 offset:1024
	ds_read_b128 v[138:141], v142 offset:2048
	ds_read_b128 v[142:145], v142 offset:3072
	ds_read_b128 v[146:149], v168
	ds_read_b128 v[150:153], v168 offset:1024
	ds_read_b128 v[154:157], v168 offset:2048
	ds_read_b128 v[168:171], v168 offset:3072
	s_add_i32 s13, 0, 0x18000
	s_add_i32 s14, 0, 0x1c000
	s_add_u32 s64, s64, s50
	s_addc_u32 s65, s65, s51
	s_mov_b32 m0, s95
	v_lshl_add_u64 v[244:245], s[64:65], 0, v[158:159]
	ds_read_b128 v[172:175], v210 offset:32768
	ds_read_b128 v[176:179], v210 offset:33792
	ds_read_b128 v[180:183], v210 offset:34816
	ds_read_b128 v[184:187], v210 offset:35840
	ds_read_b128 v[188:191], v210 offset:36864
	ds_read_b128 v[200:203], v210 offset:37888
	ds_read_b128 v[204:207], v210 offset:38912
	ds_read_b128 v[214:217], v210 offset:39936
	global_load_lds_dwordx4 v[244:245], off
	v_lshl_add_u64 v[244:245], s[64:65], 0, v[160:161]
	s_mov_b32 m0, s96
	s_nop 0
	global_load_lds_dwordx4 v[244:245], off
	s_waitcnt vmcnt(8)
	s_waitcnt lgkmcnt(0)
	s_barrier
	s_setprio 1
	s_waitcnt lgkmcnt(0)
	v_mfma_f32_16x16x32_bf16 v[126:129], v[130:133], v[172:175], v[126:129]
	v_mfma_f32_16x16x32_bf16 v[122:125], v[138:141], v[172:175], v[122:125]
	v_mfma_f32_16x16x32_bf16 v[110:113], v[130:133], v[180:183], v[110:113]
	v_mfma_f32_16x16x32_bf16 v[106:109], v[138:141], v[180:183], v[106:109]
	v_mfma_f32_16x16x32_bf16 v[94:97], v[130:133], v[188:191], v[94:97]
	v_mfma_f32_16x16x32_bf16 v[90:93], v[138:141], v[188:191], v[90:93]
	v_mfma_f32_16x16x32_bf16 v[78:81], v[130:133], v[204:207], v[78:81]
	v_mfma_f32_16x16x32_bf16 v[74:77], v[138:141], v[204:207], v[74:77]
	v_mfma_f32_16x16x32_bf16 v[126:129], v[134:137], v[176:179], v[126:129]
	v_mfma_f32_16x16x32_bf16 v[122:125], v[142:145], v[176:179], v[122:125]
	v_mfma_f32_16x16x32_bf16 v[110:113], v[134:137], v[184:187], v[110:113]
	v_mfma_f32_16x16x32_bf16 v[106:109], v[142:145], v[184:187], v[106:109]
	v_mfma_f32_16x16x32_bf16 v[94:97], v[134:137], v[200:203], v[94:97]
	v_mfma_f32_16x16x32_bf16 v[90:93], v[142:145], v[200:203], v[90:93]
	v_mfma_f32_16x16x32_bf16 v[78:81], v[134:137], v[214:217], v[78:81]
	v_mfma_f32_16x16x32_bf16 v[74:77], v[142:145], v[214:217], v[74:77]
	s_setprio 0
	s_setprio 1
	v_mfma_f32_16x16x32_bf16 v[118:121], v[146:149], v[172:175], v[118:121]
	v_mfma_f32_16x16x32_bf16 v[114:117], v[154:157], v[172:175], v[114:117]
	v_mfma_f32_16x16x32_bf16 v[102:105], v[146:149], v[180:183], v[102:105]
	v_mfma_f32_16x16x32_bf16 v[98:101], v[154:157], v[180:183], v[98:101]
	v_mfma_f32_16x16x32_bf16 v[86:89], v[146:149], v[188:191], v[86:89]
	v_mfma_f32_16x16x32_bf16 v[82:85], v[154:157], v[188:191], v[82:85]
	v_mfma_f32_16x16x32_bf16 v[70:73], v[146:149], v[204:207], v[70:73]
	v_mfma_f32_16x16x32_bf16 v[66:69], v[154:157], v[204:207], v[66:69]
	v_mfma_f32_16x16x32_bf16 v[118:121], v[150:153], v[176:179], v[118:121]
	v_mfma_f32_16x16x32_bf16 v[114:117], v[168:171], v[176:179], v[114:117]
	v_mfma_f32_16x16x32_bf16 v[102:105], v[150:153], v[184:187], v[102:105]
	v_mfma_f32_16x16x32_bf16 v[98:101], v[168:171], v[184:187], v[98:101]
	v_mfma_f32_16x16x32_bf16 v[86:89], v[150:153], v[200:203], v[86:89]
	v_mfma_f32_16x16x32_bf16 v[82:85], v[168:171], v[200:203], v[82:85]
	v_mfma_f32_16x16x32_bf16 v[70:73], v[150:153], v[214:217], v[70:73]
	v_mfma_f32_16x16x32_bf16 v[66:69], v[168:171], v[214:217], v[66:69]
	s_setprio 0
	s_barrier
; #define PG8_STAGE(bufoff, gbase, voff) do { _Pragma("unroll") for (int _i = 0; _i < 2; ++_i) \
;         __builtin_amdgcn_global_load_lds((const unsigned*)((const char*)(gbase) + (voff)[_i]), (PG8_LAS unsigned*)(lds + (bufoff) + ldsw + _i * 8192), 16, 0, 0); } while (0)
; #define PG8_LDA(dst, b, h) do { _Pragma("unroll") for (int m = 0; m < 4; ++m) _Pragma("unroll") for (int k = 0; k < 2; ++k) dst[m][k] = *(const PG8_LAS bf16x8*)(lds + PG8_SA(b, h) + aoff + m * 2048 + k * 1024); } while (0)
; #define PG8_MMA(ai, bj, At, Bt) do { __builtin_amdgcn_s_setprio(1); _Pragma("unroll") for (int m = 0; m < 4; ++m) _Pragma("unroll") for (int n = 0; n < 2; ++n) _Pragma("unroll") for (int k = 0; k < 2; ++k) \
;         acc[ai][bj][m][n] = __builtin_amdgcn_mfma_f32_16x16x32_bf16(Bt[n][k], At[m][k], acc[ai][bj][m][n], 0, 0, 0); __builtin_amdgcn_s_setprio(0); } while (0)
; #define PG8_WAIT_V(n) asm volatile("s_waitcnt vmcnt(" #n ")" ::: "memory")
; #define PG8_WAIT_L(n) asm volatile("s_waitcnt lgkmcnt(" #n ")" ::: "memory")
; #define PG8_BAR __builtin_amdgcn_s_barrier()
; #define PG8_SCHED __builtin_amdgcn_sched_barrier(0)
; template <class Epi, class Sched, bool ALIGN_EPI = false, bool SP2 = false>
; __device__ __forceinline__ void gemm_phase(PG8_LAS unsigned char* lds, const Gemm g, const Sched& S, const Epi& E, int tid_) {
;     ...
;             PG8_LDA(At, 1, 1); PG8_STAGE(PG8_SB(1, 0), b3, voffB); PG8_STAGE(PG8_SB(1, 1), b3 + hstep, voffB); PG8_STAGE(PG8_SA(1, 0), a3, voffA);
;             PG8_WAIT_V(8); PG8_WAIT_L(0); PG8_BAR; PG8_MMA(1, 0, At, B0); PG8_MMA(1, 1, At, B1); PG8_BAR; PG8_SCHED;
;     ...
;         if constexpr (ALIGN_EPI) { if (wr == 0) PG8_BAR; }
	s_add_i32 s13, s13, s92
	v_lshl_add_u64 v[232:233], v[232:233], 0, s[28:29]
	s_mov_b32 m0, s13
	ds_read_b128 v[172:175], v210 offset:49152
	ds_read_b128 v[176:179], v210 offset:50176
	ds_read_b128 v[180:183], v210 offset:51200
	ds_read_b128 v[184:187], v210 offset:52224
	ds_read_b128 v[188:191], v210 offset:53248
	ds_read_b128 v[200:203], v210 offset:54272
	ds_read_b128 v[204:207], v210 offset:55296
	ds_read_b128 v[214:217], v210 offset:56320
	global_load_lds_dwordx4 v[232:233], off
	v_lshl_add_u64 v[232:233], v[234:235], 0, s[28:29]
	s_add_i32 m0, s13, 0x2000
	s_add_i32 s13, s14, s92
	global_load_lds_dwordx4 v[232:233], off
	v_lshl_add_u64 v[232:233], v[236:237], 0, s[28:29]
	s_mov_b32 m0, s13
	s_nop 0
	global_load_lds_dwordx4 v[232:233], off
	v_lshl_add_u64 v[232:233], v[238:239], 0, s[28:29]
	s_add_i32 m0, s13, 0x2000
	s_nop 0
	global_load_lds_dwordx4 v[232:233], off
	v_lshl_add_u64 v[232:233], v[240:241], 0, s[28:29]
	s_mov_b32 m0, s97
	s_nop 0
	global_load_lds_dwordx4 v[232:233], off
	v_lshl_add_u64 v[232:233], v[242:243], 0, s[28:29]
	s_mov_b32 m0, s98
	s_nop 0
	global_load_lds_dwordx4 v[232:233], off
	s_waitcnt vmcnt(8)
	s_waitcnt lgkmcnt(0)
	s_barrier
	s_setprio 1
	s_waitcnt lgkmcnt(0)
	v_mfma_f32_16x16x32_bf16 v[62:65], v[130:133], v[172:175], v[62:65]
	v_mfma_f32_16x16x32_bf16 v[58:61], v[138:141], v[172:175], v[58:61]
	v_mfma_f32_16x16x32_bf16 v[46:49], v[130:133], v[180:183], v[46:49]
	v_mfma_f32_16x16x32_bf16 v[42:45], v[138:141], v[180:183], v[42:45]
	v_mfma_f32_16x16x32_bf16 v[30:33], v[130:133], v[188:191], v[30:33]
	v_mfma_f32_16x16x32_bf16 v[26:29], v[138:141], v[188:191], v[26:29]
	v_mfma_f32_16x16x32_bf16 v[14:17], v[130:133], v[204:207], v[14:17]
	v_mfma_f32_16x16x32_bf16 v[10:13], v[138:141], v[204:207], v[10:13]
	v_mfma_f32_16x16x32_bf16 v[62:65], v[134:137], v[176:179], v[62:65]
	v_mfma_f32_16x16x32_bf16 v[58:61], v[142:145], v[176:179], v[58:61]
	v_mfma_f32_16x16x32_bf16 v[46:49], v[134:137], v[184:187], v[46:49]
	v_mfma_f32_16x16x32_bf16 v[42:45], v[142:145], v[184:187], v[42:45]
	v_mfma_f32_16x16x32_bf16 v[30:33], v[134:137], v[200:203], v[30:33]
	v_mfma_f32_16x16x32_bf16 v[26:29], v[142:145], v[200:203], v[26:29]
	v_mfma_f32_16x16x32_bf16 v[14:17], v[134:137], v[214:217], v[14:17]
	v_mfma_f32_16x16x32_bf16 v[10:13], v[142:145], v[214:217], v[10:13]
	s_setprio 0
	s_setprio 1
	v_mfma_f32_16x16x32_bf16 v[54:57], v[146:149], v[172:175], v[54:57]
	v_mfma_f32_16x16x32_bf16 v[50:53], v[154:157], v[172:175], v[50:53]
	v_mfma_f32_16x16x32_bf16 v[38:41], v[146:149], v[180:183], v[38:41]
	v_mfma_f32_16x16x32_bf16 v[34:37], v[154:157], v[180:183], v[34:37]
	v_mfma_f32_16x16x32_bf16 v[22:25], v[146:149], v[188:191], v[22:25]
	v_mfma_f32_16x16x32_bf16 v[18:21], v[154:157], v[188:191], v[18:21]
	v_mfma_f32_16x16x32_bf16 v[6:9], v[146:149], v[204:207], v[6:9]
	v_mfma_f32_16x16x32_bf16 v[2:5], v[154:157], v[204:207], v[2:5]
	v_mfma_f32_16x16x32_bf16 v[54:57], v[150:153], v[176:179], v[54:57]
	v_mfma_f32_16x16x32_bf16 v[50:53], v[168:171], v[176:179], v[50:53]
	v_mfma_f32_16x16x32_bf16 v[38:41], v[150:153], v[184:187], v[38:41]
	v_mfma_f32_16x16x32_bf16 v[34:37], v[168:171], v[184:187], v[34:37]
	v_mfma_f32_16x16x32_bf16 v[22:25], v[150:153], v[200:203], v[22:25]
	v_mfma_f32_16x16x32_bf16 v[18:21], v[168:171], v[200:203], v[18:21]
	v_mfma_f32_16x16x32_bf16 v[6:9], v[150:153], v[214:217], v[6:9]
	v_mfma_f32_16x16x32_bf16 v[2:5], v[168:171], v[214:217], v[2:5]
	s_setprio 0
	s_barrier
	s_add_u32 s80, s80, 0x100
	s_addc_u32 s81, s81, 0
	s_add_u32 vcc_lo, vcc_lo, 0x100
	s_addc_u32 vcc_hi, vcc_hi, 0
	s_cmp_ge_i32 s74, s86
	s_mov_b32 s64, s74
	s_cbranch_scc0 .LBB0_438
	s_movk_i32 s90, 0x7ff
	s_movk_i32 s91, 0x80
	s_and_b64 vcc, exec, s[56:57]
	s_cbranch_vccz .LBB0_441

; #define PG8_STAGE(bufoff, gbase, voff) do { _Pragma("unroll") for (int _i = 0; _i < 2; ++_i) \
;         __builtin_amdgcn_global_load_lds((const unsigned*)((const char*)(gbase) + (voff)[_i]), (PG8_LAS unsigned*)(lds + (bufoff) + ldsw + _i * 8192), 16, 0, 0); } while (0)
; #define PG8_LDA(dst, b, h) do { _Pragma("unroll") for (int m = 0; m < 4; ++m) _Pragma("unroll") for (int k = 0; k < 2; ++k) dst[m][k] = *(const PG8_LAS bf16x8*)(lds + PG8_SA(b, h) + aoff + m * 2048 + k * 1024); } while (0)
; #define PG8_LDB(dst, b, h) do { _Pragma("unroll") for (int n = 0; n < 2; ++n) _Pragma("unroll") for (int k = 0; k < 2; ++k) dst[n][k] = *(const PG8_LAS bf16x8*)(lds + PG8_SB(b, h) + boff + n * 2048 + k * 1024); } while (0)
; #define PG8_MMA(ai, bj, At, Bt) do { __builtin_amdgcn_s_setprio(1); _Pragma("unroll") for (int m = 0; m < 4; ++m) _Pragma("unroll") for (int n = 0; n < 2; ++n) _Pragma("unroll") for (int k = 0; k < 2; ++k) \
;         acc[ai][bj][m][n] = __builtin_amdgcn_mfma_f32_16x16x32_bf16(Bt[n][k], At[m][k], acc[ai][bj][m][n], 0, 0, 0); __builtin_amdgcn_s_setprio(0); } while (0)
; #define PG8_WAIT_V(n) asm volatile("s_waitcnt vmcnt(" #n ")" ::: "memory")
; #define PG8_WAIT_L(n) asm volatile("s_waitcnt lgkmcnt(" #n ")" ::: "memory")
; template <class Epi, class Sched, bool ALIGN_EPI = false, bool SP2 = false>
; __device__ __forceinline__ void gemm_phase(PG8_LAS unsigned char* lds, const Gemm g, const Sched& S, const Epi& E, int tid_) {
;     ...
;             const bool last = (t == nt - 2);
;             const char* a1 = cA + (size_t)(t + 1) * kstep;
;             const char* a2 = last ? nA : cA + (size_t)(t + 2) * kstep; const char* b2 = last ? nB : cB + (size_t)(t + 2) * kstep;
;             const char* a3 = a2 + kstep; const char* b3 = b2 + kstep;
;             if (last && has_next) S.a_ready(nxt);
;             if constexpr (SP2) {
;             PG8_LDB(B0, 0, 0); PG8_LDB(B1, 0, 1); PG8_SCHED; PG8_LDA(At, 0, 0); PG8_STAGE(PG8_SA(1, 1), a1 + hstep, voffA);
;             PG8_WAIT_V(8); PG8_WAIT_L(0); PG8_BAR; PG8_MMA(0, 0, At, B0); PG8_MMA(0, 1, At, B1); PG8_BAR; PG8_SCHED;
;             PG8_LDA(At, 0, 1); PG8_STAGE(PG8_SB(0, 0), b2, voffB); PG8_STAGE(PG8_SB(0, 1), b2 + hstep, voffB); PG8_STAGE(PG8_SA(0, 0), a2, voffA);
;             PG8_WAIT_V(8); PG8_WAIT_L(0); PG8_BAR; PG8_MMA(1, 0, At, B0); PG8_MMA(1, 1, At, B1); PG8_BAR; PG8_SCHED;
.LBB0_526:
	v_add_u32_e32 v156, 0x10000, v145
	v_add_u32_e32 v172, 0x14000, v145
	ds_read_b128 v[140:143], v156
	ds_read_b128 v[148:151], v156 offset:1024
	ds_read_b128 v[152:155], v156 offset:2048
	ds_read_b128 v[156:159], v156 offset:3072
	ds_read_b128 v[160:163], v172
	ds_read_b128 v[164:167], v172 offset:1024
	ds_read_b128 v[168:171], v172 offset:2048
	ds_read_b128 v[172:175], v172 offset:3072
	s_add_u32 s21, s54, 0xfffc0080
	s_addc_u32 s56, s55, -1
	s_add_i32 s75, 0, 0x10000
	s_cmp_eq_u32 s74, 12
	s_cselect_b32 s59, s47, s56
	s_cselect_b32 s58, s70, s21
	s_cselect_b32 s57, s45, s73
	s_cselect_b32 s56, s71, s72
	s_add_i32 s21, 0, 0x14000
	v_lshl_add_u64 v[232:233], s[54:55], 0, v[138:139]
	s_add_i32 m0, s13, 0xc000
	ds_read_b128 v[176:179], v147
	ds_read_b128 v[180:183], v147 offset:1024
	ds_read_b128 v[184:187], v147 offset:2048
	ds_read_b128 v[188:191], v147 offset:3072
	ds_read_b128 v[200:203], v147 offset:4096
	ds_read_b128 v[204:207], v147 offset:5120
	ds_read_b128 v[208:211], v147 offset:6144
	ds_read_b128 v[214:217], v147 offset:7168
	global_load_lds_dwordx4 v[232:233], off
	v_lshl_add_u64 v[232:233], s[54:55], 0, v[136:137]
	s_add_i32 m0, s13, 0xe000
	s_nop 0
	global_load_lds_dwordx4 v[232:233], off
	s_waitcnt vmcnt(8)
	s_waitcnt lgkmcnt(0)
	s_barrier
	s_setprio 1
	s_waitcnt lgkmcnt(0)
	v_mfma_f32_16x16x32_bf16 v[126:129], v[140:143], v[176:179], v[126:129]
	v_mfma_f32_16x16x32_bf16 v[118:121], v[152:155], v[176:179], v[118:121]
	v_mfma_f32_16x16x32_bf16 v[110:113], v[140:143], v[184:187], v[110:113]
	v_mfma_f32_16x16x32_bf16 v[102:105], v[152:155], v[184:187], v[102:105]
	v_mfma_f32_16x16x32_bf16 v[94:97], v[140:143], v[200:203], v[94:97]
	v_mfma_f32_16x16x32_bf16 v[86:89], v[152:155], v[200:203], v[86:89]
	v_mfma_f32_16x16x32_bf16 v[78:81], v[140:143], v[208:211], v[78:81]
	v_mfma_f32_16x16x32_bf16 v[70:73], v[152:155], v[208:211], v[70:73]
	v_mfma_f32_16x16x32_bf16 v[126:129], v[148:151], v[180:183], v[126:129]
	v_mfma_f32_16x16x32_bf16 v[118:121], v[156:159], v[180:183], v[118:121]
	v_mfma_f32_16x16x32_bf16 v[110:113], v[148:151], v[188:191], v[110:113]
	v_mfma_f32_16x16x32_bf16 v[102:105], v[156:159], v[188:191], v[102:105]
	v_mfma_f32_16x16x32_bf16 v[94:97], v[148:151], v[204:207], v[94:97]
	v_mfma_f32_16x16x32_bf16 v[86:89], v[156:159], v[204:207], v[86:89]
	v_mfma_f32_16x16x32_bf16 v[78:81], v[148:151], v[214:217], v[78:81]
	v_mfma_f32_16x16x32_bf16 v[70:73], v[156:159], v[214:217], v[70:73]
	s_setprio 0
	s_setprio 1
	v_mfma_f32_16x16x32_bf16 v[122:125], v[160:163], v[176:179], v[122:125]
	v_mfma_f32_16x16x32_bf16 v[114:117], v[168:171], v[176:179], v[114:117]
	v_mfma_f32_16x16x32_bf16 v[106:109], v[160:163], v[184:187], v[106:109]
	v_mfma_f32_16x16x32_bf16 v[98:101], v[168:171], v[184:187], v[98:101]
	v_mfma_f32_16x16x32_bf16 v[90:93], v[160:163], v[200:203], v[90:93]
	v_mfma_f32_16x16x32_bf16 v[82:85], v[168:171], v[200:203], v[82:85]
	v_mfma_f32_16x16x32_bf16 v[74:77], v[160:163], v[208:211], v[74:77]
	v_mfma_f32_16x16x32_bf16 v[66:69], v[168:171], v[208:211], v[66:69]
	v_mfma_f32_16x16x32_bf16 v[122:125], v[164:167], v[180:183], v[122:125]
	v_mfma_f32_16x16x32_bf16 v[114:117], v[172:175], v[180:183], v[114:117]
	v_mfma_f32_16x16x32_bf16 v[106:109], v[164:167], v[188:191], v[106:109]
	v_mfma_f32_16x16x32_bf16 v[98:101], v[172:175], v[188:191], v[98:101]
	v_mfma_f32_16x16x32_bf16 v[90:93], v[164:167], v[204:207], v[90:93]
	v_mfma_f32_16x16x32_bf16 v[82:85], v[172:175], v[204:207], v[82:85]
	v_mfma_f32_16x16x32_bf16 v[74:77], v[164:167], v[214:217], v[74:77]
	v_mfma_f32_16x16x32_bf16 v[66:69], v[172:175], v[214:217], v[66:69]
	s_setprio 0
	s_barrier
	s_add_i32 s75, s75, s9
	v_lshl_add_u64 v[232:233], s[56:57], 0, v[0:1]
	s_mov_b32 m0, s75
	ds_read_b128 v[176:179], v147 offset:16384
	ds_read_b128 v[180:183], v147 offset:17408
	ds_read_b128 v[184:187], v147 offset:18432
	ds_read_b128 v[188:191], v147 offset:19456
	ds_read_b128 v[200:203], v147 offset:20480
	ds_read_b128 v[204:207], v147 offset:21504
	ds_read_b128 v[208:211], v147 offset:22528
	ds_read_b128 v[214:217], v147 offset:23552
	global_load_lds_dwordx4 v[232:233], off
	s_add_i32 m0, s75, 0x2000
	s_add_u32 s80, s56, 0x40000
	v_lshl_add_u64 v[234:235], s[56:57], 0, v[130:131]
	s_addc_u32 s81, s57, 0
	s_add_i32 s21, s21, s9
	global_load_lds_dwordx4 v[234:235], off
	v_lshl_add_u64 v[236:237], s[80:81], 0, v[0:1]
	s_mov_b32 m0, s21
	v_lshl_add_u64 v[238:239], s[58:59], 0, v[132:133]
	global_load_lds_dwordx4 v[236:237], off
	v_lshl_add_u64 v[236:237], s[80:81], 0, v[130:131]
	s_add_i32 m0, s21, 0x2000
	s_nop 0
	global_load_lds_dwordx4 v[236:237], off
	v_lshl_add_u64 v[236:237], s[58:59], 0, v[134:135]
	s_mov_b32 m0, s13
	s_nop 0
	global_load_lds_dwordx4 v[236:237], off
	s_mov_b32 m0, s14
	s_nop 0
	global_load_lds_dwordx4 v[238:239], off
	s_waitcnt vmcnt(8)
	s_waitcnt lgkmcnt(0)
	s_barrier
; #define PG8_STAGE(bufoff, gbase, voff) do { _Pragma("unroll") for (int _i = 0; _i < 2; ++_i) \
;         __builtin_amdgcn_global_load_lds((const unsigned*)((const char*)(gbase) + (voff)[_i]), (PG8_LAS unsigned*)(lds + (bufoff) + ldsw + _i * 8192), 16, 0, 0); } while (0)
; #define PG8_LDA(dst, b, h) do { _Pragma("unroll") for (int m = 0; m < 4; ++m) _Pragma("unroll") for (int k = 0; k < 2; ++k) dst[m][k] = *(const PG8_LAS bf16x8*)(lds + PG8_SA(b, h) + aoff + m * 2048 + k * 1024); } while (0)
; #define PG8_LDB(dst, b, h) do { _Pragma("unroll") for (int n = 0; n < 2; ++n) _Pragma("unroll") for (int k = 0; k < 2; ++k) dst[n][k] = *(const PG8_LAS bf16x8*)(lds + PG8_SB(b, h) + boff + n * 2048 + k * 1024); } while (0)
; #define PG8_MMA(ai, bj, At, Bt) do { __builtin_amdgcn_s_setprio(1); _Pragma("unroll") for (int m = 0; m < 4; ++m) _Pragma("unroll") for (int n = 0; n < 2; ++n) _Pragma("unroll") for (int k = 0; k < 2; ++k) \
;         acc[ai][bj][m][n] = __builtin_amdgcn_mfma_f32_16x16x32_bf16(Bt[n][k], At[m][k], acc[ai][bj][m][n], 0, 0, 0); __builtin_amdgcn_s_setprio(0); } while (0)
; #define PG8_WAIT_V(n) asm volatile("s_waitcnt vmcnt(" #n ")" ::: "memory")
; #define PG8_WAIT_L(n) asm volatile("s_waitcnt lgkmcnt(" #n ")" ::: "memory")
; #define PG8_BAR __builtin_amdgcn_s_barrier()
; #define PG8_SCHED __builtin_amdgcn_sched_barrier(0)
; template <class Epi, class Sched, bool ALIGN_EPI = false, bool SP2 = false>
; __device__ __forceinline__ void gemm_phase(PG8_LAS unsigned char* lds, const Gemm g, const Sched& S, const Epi& E, int tid_) {
;     ...
;             PG8_WAIT_V(8); PG8_WAIT_L(0); PG8_BAR; PG8_MMA(1, 0, At, B0); PG8_MMA(1, 1, At, B1); PG8_BAR; PG8_SCHED;
;             PG8_LDB(B0, 1, 0); PG8_LDB(B1, 1, 1); PG8_SCHED; PG8_LDA(At, 1, 0); PG8_STAGE(PG8_SA(0, 1), a2 + hstep, voffA);
;             PG8_WAIT_V(8); PG8_WAIT_L(0); PG8_BAR; PG8_MMA(0, 0, At, B0); PG8_MMA(0, 1, At, B1); PG8_BAR; PG8_SCHED;
	s_setprio 1
	s_waitcnt lgkmcnt(0)
	v_mfma_f32_16x16x32_bf16 v[62:65], v[140:143], v[176:179], v[62:65]
	v_mfma_f32_16x16x32_bf16 v[54:57], v[152:155], v[176:179], v[54:57]
	v_mfma_f32_16x16x32_bf16 v[46:49], v[140:143], v[184:187], v[46:49]
	v_mfma_f32_16x16x32_bf16 v[38:41], v[152:155], v[184:187], v[38:41]
	v_mfma_f32_16x16x32_bf16 v[30:33], v[140:143], v[200:203], v[30:33]
	v_mfma_f32_16x16x32_bf16 v[22:25], v[152:155], v[200:203], v[22:25]
	v_mfma_f32_16x16x32_bf16 v[14:17], v[140:143], v[208:211], v[14:17]
	v_mfma_f32_16x16x32_bf16 v[6:9], v[152:155], v[208:211], v[6:9]
	v_mfma_f32_16x16x32_bf16 v[62:65], v[148:151], v[180:183], v[62:65]
	v_mfma_f32_16x16x32_bf16 v[54:57], v[156:159], v[180:183], v[54:57]
	v_mfma_f32_16x16x32_bf16 v[46:49], v[148:151], v[188:191], v[46:49]
	v_mfma_f32_16x16x32_bf16 v[38:41], v[156:159], v[188:191], v[38:41]
	v_mfma_f32_16x16x32_bf16 v[30:33], v[148:151], v[204:207], v[30:33]
	v_mfma_f32_16x16x32_bf16 v[22:25], v[156:159], v[204:207], v[22:25]
	v_mfma_f32_16x16x32_bf16 v[14:17], v[148:151], v[214:217], v[14:17]
	v_mfma_f32_16x16x32_bf16 v[6:9], v[156:159], v[214:217], v[6:9]
	s_setprio 0
	s_setprio 1
	v_mfma_f32_16x16x32_bf16 v[58:61], v[160:163], v[176:179], v[58:61]
	v_mfma_f32_16x16x32_bf16 v[50:53], v[168:171], v[176:179], v[50:53]
	v_mfma_f32_16x16x32_bf16 v[42:45], v[160:163], v[184:187], v[42:45]
	v_mfma_f32_16x16x32_bf16 v[34:37], v[168:171], v[184:187], v[34:37]
	v_mfma_f32_16x16x32_bf16 v[26:29], v[160:163], v[200:203], v[26:29]
	v_mfma_f32_16x16x32_bf16 v[18:21], v[168:171], v[200:203], v[18:21]
	v_mfma_f32_16x16x32_bf16 v[10:13], v[160:163], v[208:211], v[10:13]
	v_mfma_f32_16x16x32_bf16 v[2:5], v[168:171], v[208:211], v[2:5]
	v_mfma_f32_16x16x32_bf16 v[58:61], v[164:167], v[180:183], v[58:61]
	v_mfma_f32_16x16x32_bf16 v[50:53], v[172:175], v[180:183], v[50:53]
	v_mfma_f32_16x16x32_bf16 v[42:45], v[164:167], v[188:191], v[42:45]
	v_mfma_f32_16x16x32_bf16 v[34:37], v[172:175], v[188:191], v[34:37]
	v_mfma_f32_16x16x32_bf16 v[26:29], v[164:167], v[204:207], v[26:29]
	v_mfma_f32_16x16x32_bf16 v[18:21], v[172:175], v[204:207], v[18:21]
	v_mfma_f32_16x16x32_bf16 v[10:13], v[164:167], v[214:217], v[10:13]
	v_mfma_f32_16x16x32_bf16 v[2:5], v[172:175], v[214:217], v[2:5]
	s_setprio 0
	s_barrier
	v_add_u32_e32 v156, 0x18000, v145
	v_add_u32_e32 v172, 0x1c000, v145
	ds_read_b128 v[140:143], v156
	ds_read_b128 v[148:151], v156 offset:1024
	ds_read_b128 v[152:155], v156 offset:2048
	ds_read_b128 v[156:159], v156 offset:3072
	ds_read_b128 v[160:163], v172
	ds_read_b128 v[164:167], v172 offset:1024
	ds_read_b128 v[168:171], v172 offset:2048
	ds_read_b128 v[172:175], v172 offset:3072
	s_add_i32 s21, 0, 0x18000
	s_add_i32 s75, 0, 0x1c000
	s_add_u32 s58, s58, 0x40000
	s_addc_u32 s59, s59, 0
	s_mov_b32 m0, s15
	v_lshl_add_u64 v[240:241], s[58:59], 0, v[134:135]
	ds_read_b128 v[176:179], v147 offset:32768
	ds_read_b128 v[180:183], v147 offset:33792
	ds_read_b128 v[184:187], v147 offset:34816
	ds_read_b128 v[188:191], v147 offset:35840
	ds_read_b128 v[200:203], v147 offset:36864
	ds_read_b128 v[204:207], v147 offset:37888
	ds_read_b128 v[208:211], v147 offset:38912
	ds_read_b128 v[214:217], v147 offset:39936
	global_load_lds_dwordx4 v[240:241], off
	v_lshl_add_u64 v[240:241], s[58:59], 0, v[132:133]
	s_mov_b32 m0, s60
	s_nop 0
	global_load_lds_dwordx4 v[240:241], off
	s_waitcnt vmcnt(8)
	s_waitcnt lgkmcnt(0)
	s_barrier
	s_setprio 1
	s_waitcnt lgkmcnt(0)
	v_mfma_f32_16x16x32_bf16 v[126:129], v[140:143], v[176:179], v[126:129]
	v_mfma_f32_16x16x32_bf16 v[118:121], v[152:155], v[176:179], v[118:121]
	v_mfma_f32_16x16x32_bf16 v[110:113], v[140:143], v[184:187], v[110:113]
	v_mfma_f32_16x16x32_bf16 v[102:105], v[152:155], v[184:187], v[102:105]
	v_mfma_f32_16x16x32_bf16 v[94:97], v[140:143], v[200:203], v[94:97]
	v_mfma_f32_16x16x32_bf16 v[86:89], v[152:155], v[200:203], v[86:89]
	v_mfma_f32_16x16x32_bf16 v[78:81], v[140:143], v[208:211], v[78:81]
	v_mfma_f32_16x16x32_bf16 v[70:73], v[152:155], v[208:211], v[70:73]
	v_mfma_f32_16x16x32_bf16 v[126:129], v[148:151], v[180:183], v[126:129]
	v_mfma_f32_16x16x32_bf16 v[118:121], v[156:159], v[180:183], v[118:121]
	v_mfma_f32_16x16x32_bf16 v[110:113], v[148:151], v[188:191], v[110:113]
	v_mfma_f32_16x16x32_bf16 v[102:105], v[156:159], v[188:191], v[102:105]
	v_mfma_f32_16x16x32_bf16 v[94:97], v[148:151], v[204:207], v[94:97]
	v_mfma_f32_16x16x32_bf16 v[86:89], v[156:159], v[204:207], v[86:89]
	v_mfma_f32_16x16x32_bf16 v[78:81], v[148:151], v[214:217], v[78:81]
	v_mfma_f32_16x16x32_bf16 v[70:73], v[156:159], v[214:217], v[70:73]
	s_setprio 0
	s_setprio 1
	v_mfma_f32_16x16x32_bf16 v[122:125], v[160:163], v[176:179], v[122:125]
	v_mfma_f32_16x16x32_bf16 v[114:117], v[168:171], v[176:179], v[114:117]
	v_mfma_f32_16x16x32_bf16 v[106:109], v[160:163], v[184:187], v[106:109]
	v_mfma_f32_16x16x32_bf16 v[98:101], v[168:171], v[184:187], v[98:101]
	v_mfma_f32_16x16x32_bf16 v[90:93], v[160:163], v[200:203], v[90:93]
	v_mfma_f32_16x16x32_bf16 v[82:85], v[168:171], v[200:203], v[82:85]
	v_mfma_f32_16x16x32_bf16 v[74:77], v[160:163], v[208:211], v[74:77]
	v_mfma_f32_16x16x32_bf16 v[66:69], v[168:171], v[208:211], v[66:69]
	v_mfma_f32_16x16x32_bf16 v[122:125], v[164:167], v[180:183], v[122:125]
	v_mfma_f32_16x16x32_bf16 v[114:117], v[172:175], v[180:183], v[114:117]
	v_mfma_f32_16x16x32_bf16 v[106:109], v[164:167], v[188:191], v[106:109]
	v_mfma_f32_16x16x32_bf16 v[98:101], v[172:175], v[188:191], v[98:101]
	v_mfma_f32_16x16x32_bf16 v[90:93], v[164:167], v[204:207], v[90:93]
	v_mfma_f32_16x16x32_bf16 v[82:85], v[172:175], v[204:207], v[82:85]
	v_mfma_f32_16x16x32_bf16 v[74:77], v[164:167], v[214:217], v[74:77]
	v_mfma_f32_16x16x32_bf16 v[66:69], v[172:175], v[214:217], v[66:69]
	s_setprio 0
	s_barrier
; #define PG8_STAGE(bufoff, gbase, voff) do { _Pragma("unroll") for (int _i = 0; _i < 2; ++_i) \
;         __builtin_amdgcn_global_load_lds((const unsigned*)((const char*)(gbase) + (voff)[_i]), (PG8_LAS unsigned*)(lds + (bufoff) + ldsw + _i * 8192), 16, 0, 0); } while (0)
; #define PG8_LDA(dst, b, h) do { _Pragma("unroll") for (int m = 0; m < 4; ++m) _Pragma("unroll") for (int k = 0; k < 2; ++k) dst[m][k] = *(const PG8_LAS bf16x8*)(lds + PG8_SA(b, h) + aoff + m * 2048 + k * 1024); } while (0)
; #define PG8_MMA(ai, bj, At, Bt) do { __builtin_amdgcn_s_setprio(1); _Pragma("unroll") for (int m = 0; m < 4; ++m) _Pragma("unroll") for (int n = 0; n < 2; ++n) _Pragma("unroll") for (int k = 0; k < 2; ++k) \
;         acc[ai][bj][m][n] = __builtin_amdgcn_mfma_f32_16x16x32_bf16(Bt[n][k], At[m][k], acc[ai][bj][m][n], 0, 0, 0); __builtin_amdgcn_s_setprio(0); } while (0)
; #define PG8_WAIT_V(n) asm volatile("s_waitcnt vmcnt(" #n ")" ::: "memory")
; #define PG8_WAIT_L(n) asm volatile("s_waitcnt lgkmcnt(" #n ")" ::: "memory")
; #define PG8_BAR __builtin_amdgcn_s_barrier()
; #define PG8_SCHED __builtin_amdgcn_sched_barrier(0)
; template <class Epi, class Sched, bool ALIGN_EPI = false, bool SP2 = false>
; __device__ __forceinline__ void gemm_phase(PG8_LAS unsigned char* lds, const Gemm g, const Sched& S, const Epi& E, int tid_) {
;     ...
;             PG8_LDA(At, 1, 1); PG8_STAGE(PG8_SB(1, 0), b3, voffB); PG8_STAGE(PG8_SB(1, 1), b3 + hstep, voffB); PG8_STAGE(PG8_SA(1, 0), a3, voffA);
;             PG8_WAIT_V(8); PG8_WAIT_L(0); PG8_BAR; PG8_MMA(1, 0, At, B0); PG8_MMA(1, 1, At, B1); PG8_BAR; PG8_SCHED;
;     ...
;         if constexpr (ALIGN_EPI) { if (wr == 0) PG8_BAR; }
	s_add_i32 s21, s21, s9
	v_lshl_add_u64 v[232:233], v[232:233], 0, s[28:29]
	s_mov_b32 m0, s21
	ds_read_b128 v[176:179], v147 offset:49152
	ds_read_b128 v[180:183], v147 offset:50176
	ds_read_b128 v[184:187], v147 offset:51200
	ds_read_b128 v[188:191], v147 offset:52224
	ds_read_b128 v[200:203], v147 offset:53248
	ds_read_b128 v[204:207], v147 offset:54272
	ds_read_b128 v[208:211], v147 offset:55296
	ds_read_b128 v[214:217], v147 offset:56320
	global_load_lds_dwordx4 v[232:233], off
	s_add_i32 m0, s21, 0x2000
	s_add_u32 s56, s56, 0x40080
	v_lshl_add_u64 v[232:233], v[234:235], 0, s[28:29]
	s_addc_u32 s57, s57, 0
	s_add_i32 s21, s75, s9
	global_load_lds_dwordx4 v[232:233], off
	v_lshl_add_u64 v[232:233], s[56:57], 0, v[0:1]
	s_mov_b32 m0, s21
	s_nop 0
	global_load_lds_dwordx4 v[232:233], off
	v_lshl_add_u64 v[232:233], s[56:57], 0, v[130:131]
	s_add_i32 m0, s21, 0x2000
	s_nop 0
	global_load_lds_dwordx4 v[232:233], off
	v_lshl_add_u64 v[232:233], v[236:237], 0, s[28:29]
	s_mov_b32 m0, s61
	s_nop 0
	global_load_lds_dwordx4 v[232:233], off
	v_lshl_add_u64 v[232:233], v[238:239], 0, s[28:29]
	s_mov_b32 m0, s64
	s_nop 0
	global_load_lds_dwordx4 v[232:233], off
	s_waitcnt vmcnt(8)
	s_waitcnt lgkmcnt(0)
	s_barrier
	s_setprio 1
	s_waitcnt lgkmcnt(0)
	v_mfma_f32_16x16x32_bf16 v[62:65], v[140:143], v[176:179], v[62:65]
	v_mfma_f32_16x16x32_bf16 v[54:57], v[152:155], v[176:179], v[54:57]
	v_mfma_f32_16x16x32_bf16 v[46:49], v[140:143], v[184:187], v[46:49]
	v_mfma_f32_16x16x32_bf16 v[38:41], v[152:155], v[184:187], v[38:41]
	v_mfma_f32_16x16x32_bf16 v[30:33], v[140:143], v[200:203], v[30:33]
	v_mfma_f32_16x16x32_bf16 v[22:25], v[152:155], v[200:203], v[22:25]
	v_mfma_f32_16x16x32_bf16 v[14:17], v[140:143], v[208:211], v[14:17]
	v_mfma_f32_16x16x32_bf16 v[6:9], v[152:155], v[208:211], v[6:9]
	v_mfma_f32_16x16x32_bf16 v[62:65], v[148:151], v[180:183], v[62:65]
	v_mfma_f32_16x16x32_bf16 v[54:57], v[156:159], v[180:183], v[54:57]
	v_mfma_f32_16x16x32_bf16 v[46:49], v[148:151], v[188:191], v[46:49]
	v_mfma_f32_16x16x32_bf16 v[38:41], v[156:159], v[188:191], v[38:41]
	v_mfma_f32_16x16x32_bf16 v[30:33], v[148:151], v[204:207], v[30:33]
	v_mfma_f32_16x16x32_bf16 v[22:25], v[156:159], v[204:207], v[22:25]
	v_mfma_f32_16x16x32_bf16 v[14:17], v[148:151], v[214:217], v[14:17]
	v_mfma_f32_16x16x32_bf16 v[6:9], v[156:159], v[214:217], v[6:9]
	s_setprio 0
	s_setprio 1
	v_mfma_f32_16x16x32_bf16 v[58:61], v[160:163], v[176:179], v[58:61]
	v_mfma_f32_16x16x32_bf16 v[50:53], v[168:171], v[176:179], v[50:53]
	v_mfma_f32_16x16x32_bf16 v[42:45], v[160:163], v[184:187], v[42:45]
	v_mfma_f32_16x16x32_bf16 v[34:37], v[168:171], v[184:187], v[34:37]
	v_mfma_f32_16x16x32_bf16 v[26:29], v[160:163], v[200:203], v[26:29]
	v_mfma_f32_16x16x32_bf16 v[18:21], v[168:171], v[200:203], v[18:21]
	v_mfma_f32_16x16x32_bf16 v[10:13], v[160:163], v[208:211], v[10:13]
	v_mfma_f32_16x16x32_bf16 v[2:5], v[168:171], v[208:211], v[2:5]
	v_mfma_f32_16x16x32_bf16 v[58:61], v[164:167], v[180:183], v[58:61]
	v_mfma_f32_16x16x32_bf16 v[50:53], v[172:175], v[180:183], v[50:53]
	v_mfma_f32_16x16x32_bf16 v[42:45], v[164:167], v[188:191], v[42:45]
	v_mfma_f32_16x16x32_bf16 v[34:37], v[172:175], v[188:191], v[34:37]
	v_mfma_f32_16x16x32_bf16 v[26:29], v[164:167], v[204:207], v[26:29]
	v_mfma_f32_16x16x32_bf16 v[18:21], v[172:175], v[204:207], v[18:21]
	v_mfma_f32_16x16x32_bf16 v[10:13], v[164:167], v[214:217], v[10:13]
	v_mfma_f32_16x16x32_bf16 v[2:5], v[172:175], v[214:217], v[2:5]
	s_setprio 0
	s_barrier
	s_add_i32 s74, s74, 2
	s_add_u32 s72, s72, 0x100
	s_addc_u32 s73, s73, 0
	s_add_u32 s54, s54, 0x100
	s_addc_u32 s55, s55, 0
	s_cmp_gt_u32 s74, 13
	s_cbranch_scc0 .LBB0_526
	s_and_b64 vcc, exec, s[42:43]
	s_cbranch_vccz .LBB0_529
	s_barrier
